# PG K-loop: first iteration of tiles 2..16 peeled without the two leading vmcnt(8) waits so epilogue stores need not retire before the first MFMA segments
# speedup vs baseline: 1.0023x; 1.0023x over previous
; #define PG8_STAGE(bufoff, gbase, voff) do { _Pragma("unroll") for (int _i = 0; _i < 2; ++_i) \
;         __builtin_amdgcn_global_load_lds((const unsigned*)((const char*)(gbase) + (voff)[_i]), (LAS unsigned*)(lds + (bufoff) + ldsw + _i * 8192), 16, 0, 0); } while (0)
; #define PG8_LDA(dst, b, h) do { _Pragma("unroll") for (int m = 0; m < 4; ++m) _Pragma("unroll") for (int k = 0; k < 2; ++k) dst[m][k] = *(const LAS bf16x8*)(lds + PG8_SA(b, h) + aoff + m * 2048 + k * 1024); } while (0)
; #define PG8_LDB(dst, b, h) do { _Pragma("unroll") for (int n = 0; n < 2; ++n) _Pragma("unroll") for (int k = 0; k < 2; ++k) dst[n][k] = *(const LAS bf16x8*)(lds + PG8_SB(b, h) + boff + n * 2048 + k * 1024); } while (0)
; #define PG8_WAIT_V(n) asm volatile("s_waitcnt vmcnt(" #n ")" ::: "memory")
; #define PG8_WAIT_L(n) asm volatile("s_waitcnt lgkmcnt(" #n ")" ::: "memory")
; #define PG8_BAR __builtin_amdgcn_s_barrier()
; #define PG8_SCHED __builtin_amdgcn_sched_barrier(0)
; template <class Epi, class Sched, bool ALIGN_EPI>
; __device__ __forceinline__ void gemm_phase(LAS unsigned char* lds, const Gemm g, const Sched& S, const Epi& E) {
;     ...
;         const bool has_next = S.next(ui + 1, nxt);
;         const char* nA = has_next ? (const char*)g.A + (size_t)nxt.pm * tstepA : cA; const char* nB = has_next ? (const char*)g.Bt + (size_t)nxt.pn * tstepB : cB;
;         for (int t = 0; t < nt; t += 2) {
;             const bool last = (t == nt - 2);
;             const char* a1 = cA + (size_t)(t + 1) * kstep;
;             const char* a2 = last ? nA : cA + (size_t)(t + 2) * kstep; const char* b2 = last ? nB : cB + (size_t)(t + 2) * kstep;
;             const char* a3 = a2 + kstep; const char* b3 = b2 + kstep;
;             PG8_LDB(B0, 0, 0); PG8_LDB(B1, 0, 1); PG8_SCHED; PG8_LDA(At, 0, 0); PG8_STAGE(PG8_SA(1, 1), a1 + hstepA, voffA);
;             PG8_WAIT_V(8); PG8_WAIT_L(0); PG8_BAR; PG8_MMA(0, 0, At, B0); PG8_MMA(0, 1, At, B1); PG8_BAR; PG8_SCHED;
;     ...
; #pragma unroll
;         for (int a = 0; a < 2; ++a)
; #pragma unroll
;             for (int b = 0; b < 2; ++b)
; #pragma unroll
;                 for (int m = 0; m < 4; ++m)
; #pragma unroll
;                     for (int n = 0; n < 2; ++n) acc[a][b][m][n] = (f32x4){0.f, 0.f, 0.f, 0.f};
;         cur = nxt; cA = nA; cB = nB; ++ui;
.LBB0_286:
	s_ashr_i32 s23, s22, 31
	s_lshl_b64 s[38:39], s[22:23], 19
	s_add_u32 s38, s48, s38
	s_addc_u32 s39, s49, s39
	s_and_b64 s[40:41], s[42:43], exec
	s_cselect_b32 s23, s39, s45
	s_cselect_b32 s85, s38, s44
	s_ashr_i32 s21, s20, 31
	s_lshl_b64 s[40:41], s[20:21], 19
	s_add_u32 s40, s50, s40
	s_addc_u32 s41, s51, s41
	s_and_b64 s[54:55], s[42:43], exec
	s_cselect_b32 s21, s41, s47
	s_cselect_b32 s86, s40, s46
	s_add_u32 s44, s44, 0x40080
	s_addc_u32 s45, s45, 0
	s_add_u32 s87, s46, 0x100
	v_mov_b32_e32 v0, 0
	s_addc_u32 s90, s47, 0
	s_mov_b32 s91, -2
	v_mov_b32_e32 v1, v0
	v_mov_b32_e32 v2, v0
	v_mov_b32_e32 v3, v0
	v_mov_b32_e32 v4, v0
	v_mov_b32_e32 v5, v0
	v_mov_b32_e32 v6, v0
	v_mov_b32_e32 v7, v0
	v_mov_b32_e32 v12, v0
	v_mov_b32_e32 v13, v0
	v_mov_b32_e32 v14, v0
	v_mov_b32_e32 v15, v0
	v_mov_b32_e32 v20, v0
	v_mov_b32_e32 v21, v0
	v_mov_b32_e32 v22, v0
	v_mov_b32_e32 v23, v0
	v_mov_b32_e32 v28, v0
	v_mov_b32_e32 v29, v0
	v_mov_b32_e32 v30, v0
	v_mov_b32_e32 v31, v0
	v_mov_b32_e32 v36, v0
	v_mov_b32_e32 v37, v0
	v_mov_b32_e32 v38, v0
	v_mov_b32_e32 v39, v0
	v_mov_b32_e32 v44, v0
	v_mov_b32_e32 v45, v0
	v_mov_b32_e32 v46, v0
	v_mov_b32_e32 v47, v0
	v_mov_b32_e32 v52, v0
	v_mov_b32_e32 v53, v0
	v_mov_b32_e32 v54, v0
	v_mov_b32_e32 v55, v0
	v_mov_b32_e32 v8, v0
	v_mov_b32_e32 v9, v0
	v_mov_b32_e32 v10, v0
	v_mov_b32_e32 v11, v0
	v_mov_b32_e32 v16, v0
	v_mov_b32_e32 v17, v0
	v_mov_b32_e32 v18, v0
	v_mov_b32_e32 v19, v0
	v_mov_b32_e32 v24, v0
	v_mov_b32_e32 v25, v0
	v_mov_b32_e32 v26, v0
	v_mov_b32_e32 v27, v0
	v_mov_b32_e32 v32, v0
	v_mov_b32_e32 v33, v0
	v_mov_b32_e32 v34, v0
	v_mov_b32_e32 v35, v0
	v_mov_b32_e32 v40, v0
	v_mov_b32_e32 v41, v0
	v_mov_b32_e32 v42, v0
	v_mov_b32_e32 v43, v0
	v_mov_b32_e32 v48, v0
	v_mov_b32_e32 v49, v0
	v_mov_b32_e32 v50, v0
	v_mov_b32_e32 v51, v0
	v_mov_b32_e32 v56, v0
	v_mov_b32_e32 v57, v0
	v_mov_b32_e32 v58, v0
	v_mov_b32_e32 v59, v0
	v_mov_b32_e32 v60, v0
	v_mov_b32_e32 v61, v0
	v_mov_b32_e32 v62, v0
	v_mov_b32_e32 v63, v0
	v_mov_b32_e32 v64, v0
	v_mov_b32_e32 v65, v0
	v_mov_b32_e32 v66, v0
	v_mov_b32_e32 v67, v0
	v_mov_b32_e32 v68, v0
	v_mov_b32_e32 v69, v0
	v_mov_b32_e32 v70, v0
	v_mov_b32_e32 v71, v0
	v_mov_b32_e32 v80, v0
	v_mov_b32_e32 v81, v0
	v_mov_b32_e32 v82, v0
	v_mov_b32_e32 v83, v0
	v_mov_b32_e32 v84, v0
	v_mov_b32_e32 v85, v0
	v_mov_b32_e32 v86, v0
	v_mov_b32_e32 v87, v0
	v_mov_b32_e32 v96, v0
	v_mov_b32_e32 v97, v0
	v_mov_b32_e32 v98, v0
	v_mov_b32_e32 v99, v0
	v_mov_b32_e32 v100, v0
	v_mov_b32_e32 v101, v0
	v_mov_b32_e32 v102, v0
	v_mov_b32_e32 v103, v0
	v_mov_b32_e32 v112, v0
	v_mov_b32_e32 v113, v0
	v_mov_b32_e32 v114, v0
	v_mov_b32_e32 v115, v0
	v_mov_b32_e32 v116, v0
	v_mov_b32_e32 v117, v0
	v_mov_b32_e32 v118, v0
	v_mov_b32_e32 v119, v0
	v_mov_b32_e32 v72, v0
	v_mov_b32_e32 v73, v0
	v_mov_b32_e32 v74, v0
	v_mov_b32_e32 v75, v0
	v_mov_b32_e32 v76, v0
	v_mov_b32_e32 v77, v0
	v_mov_b32_e32 v78, v0
	v_mov_b32_e32 v79, v0
	v_mov_b32_e32 v88, v0
	v_mov_b32_e32 v89, v0
	v_mov_b32_e32 v90, v0
	v_mov_b32_e32 v91, v0
	v_mov_b32_e32 v92, v0
	v_mov_b32_e32 v93, v0
	v_mov_b32_e32 v94, v0
	v_mov_b32_e32 v95, v0
	v_mov_b32_e32 v104, v0
	v_mov_b32_e32 v105, v0
	v_mov_b32_e32 v106, v0
	v_mov_b32_e32 v107, v0
	v_mov_b32_e32 v108, v0
	v_mov_b32_e32 v109, v0
	v_mov_b32_e32 v110, v0
	v_mov_b32_e32 v111, v0
	v_mov_b32_e32 v136, v0
	v_mov_b32_e32 v137, v0
	v_mov_b32_e32 v138, v0
	v_mov_b32_e32 v139, v0
	v_mov_b32_e32 v140, v0
	v_mov_b32_e32 v141, v0
	v_mov_b32_e32 v142, v0
	v_mov_b32_e32 v143, v0
	s_cmp_eq_u32 s80, 1
	s_cbranch_scc1 .LBB0_287
	s_add_u32 s46, s44, 0xfffc0080
	s_addc_u32 s47, s45, -1
	s_add_i32 s92, 0, 0x10000
	s_cmp_eq_u32 s91, 12
	s_cselect_b32 s55, s23, s47
	s_cselect_b32 s54, s85, s46
	s_cselect_b32 s47, s21, s90
	s_cselect_b32 s46, s86, s87
	s_add_i32 s4, 0, 0x14000
	v_add_u32_e32 v132, s92, v160
	v_add_u32_e32 v170, s4, v160
	ds_read_b128 v[120:123], v132
	ds_read_b128 v[124:127], v132 offset:1024
	ds_read_b128 v[128:131], v132 offset:2048
	ds_read_b128 v[132:135], v132 offset:3072
	ds_read_b128 v[154:157], v170
	ds_read_b128 v[162:165], v170 offset:1024
	ds_read_b128 v[166:169], v170 offset:2048
	ds_read_b128 v[170:173], v170 offset:3072
	v_lshl_add_u64 v[190:191], s[44:45], 0, v[150:151]
	s_add_i32 m0, s53, 0xc000
	ds_read_b128 v[174:177], v161
	ds_read_b128 v[178:181], v161 offset:1024
	ds_read_b128 v[182:185], v161 offset:2048
	ds_read_b128 v[186:189], v161 offset:3072
	ds_read_b128 v[194:197], v161 offset:4096
	ds_read_b128 v[198:201], v161 offset:5120
	ds_read_b128 v[202:205], v161 offset:6144
	ds_read_b128 v[212:215], v161 offset:7168
	global_load_lds_dwordx4 v[190:191], off
	v_lshl_add_u64 v[190:191], s[44:45], 0, v[152:153]
	s_add_i32 m0, s53, 0xe000
	s_nop 0
	global_load_lds_dwordx4 v[190:191], off
	s_waitcnt lgkmcnt(0)
	s_barrier
; #define PG8_STAGE(bufoff, gbase, voff) do { _Pragma("unroll") for (int _i = 0; _i < 2; ++_i) \
;         __builtin_amdgcn_global_load_lds((const unsigned*)((const char*)(gbase) + (voff)[_i]), (LAS unsigned*)(lds + (bufoff) + ldsw + _i * 8192), 16, 0, 0); } while (0)
; #define PG8_LDA(dst, b, h) do { _Pragma("unroll") for (int m = 0; m < 4; ++m) _Pragma("unroll") for (int k = 0; k < 2; ++k) dst[m][k] = *(const LAS bf16x8*)(lds + PG8_SA(b, h) + aoff + m * 2048 + k * 1024); } while (0)
; #define PG8_MMA(ai, bj, At, Bt) do { __builtin_amdgcn_s_setprio(1); _Pragma("unroll") for (int m = 0; m < 4; ++m) _Pragma("unroll") for (int n = 0; n < 2; ++n) _Pragma("unroll") for (int k = 0; k < 2; ++k) \
;         acc[ai][bj][m][n] = __builtin_amdgcn_mfma_f32_16x16x32_bf16(Bt[n][k], At[m][k], acc[ai][bj][m][n], 0, 0, 0); __builtin_amdgcn_s_setprio(0); } while (0)
; #define PG8_WAIT_V(n) asm volatile("s_waitcnt vmcnt(" #n ")" ::: "memory")
; #define PG8_WAIT_L(n) asm volatile("s_waitcnt lgkmcnt(" #n ")" ::: "memory")
; #define PG8_BAR __builtin_amdgcn_s_barrier()
; #define PG8_SCHED __builtin_amdgcn_sched_barrier(0)
; template <class Epi, class Sched, bool ALIGN_EPI>
; __device__ __forceinline__ void gemm_phase(LAS unsigned char* lds, const Gemm g, const Sched& S, const Epi& E) {
;     ...
;             PG8_WAIT_V(8); PG8_WAIT_L(0); PG8_BAR; PG8_MMA(0, 0, At, B0); PG8_MMA(0, 1, At, B1); PG8_BAR; PG8_SCHED;
;             PG8_LDA(At, 0, 1); PG8_STAGE(PG8_SB(0, 0), b2, voffB); PG8_STAGE(PG8_SB(0, 1), b2 + hstepB, voffB); PG8_STAGE(PG8_SA(0, 0), a2, voffA);
;             PG8_WAIT_V(8); PG8_WAIT_L(0); PG8_BAR; PG8_MMA(1, 0, At, B0); PG8_MMA(1, 1, At, B1); PG8_BAR; PG8_SCHED;
	s_setprio 1
	s_waitcnt lgkmcnt(0)
	v_mfma_f32_16x16x32_bf16 v[140:143], v[120:123], v[174:177], v[140:143]
	v_mfma_f32_16x16x32_bf16 v[136:139], v[128:131], v[174:177], v[136:139]
	v_mfma_f32_16x16x32_bf16 v[108:111], v[120:123], v[182:185], v[108:111]
	v_mfma_f32_16x16x32_bf16 v[104:107], v[128:131], v[182:185], v[104:107]
	v_mfma_f32_16x16x32_bf16 v[92:95], v[120:123], v[194:197], v[92:95]
	v_mfma_f32_16x16x32_bf16 v[88:91], v[128:131], v[194:197], v[88:91]
	v_mfma_f32_16x16x32_bf16 v[76:79], v[120:123], v[202:205], v[76:79]
	v_mfma_f32_16x16x32_bf16 v[72:75], v[128:131], v[202:205], v[72:75]
	v_mfma_f32_16x16x32_bf16 v[140:143], v[124:127], v[178:181], v[140:143]
	v_mfma_f32_16x16x32_bf16 v[136:139], v[132:135], v[178:181], v[136:139]
	v_mfma_f32_16x16x32_bf16 v[108:111], v[124:127], v[186:189], v[108:111]
	v_mfma_f32_16x16x32_bf16 v[104:107], v[132:135], v[186:189], v[104:107]
	v_mfma_f32_16x16x32_bf16 v[92:95], v[124:127], v[198:201], v[92:95]
	v_mfma_f32_16x16x32_bf16 v[88:91], v[132:135], v[198:201], v[88:91]
	v_mfma_f32_16x16x32_bf16 v[76:79], v[124:127], v[212:215], v[76:79]
	v_mfma_f32_16x16x32_bf16 v[72:75], v[132:135], v[212:215], v[72:75]
	s_setprio 0
	s_setprio 1
	v_mfma_f32_16x16x32_bf16 v[116:119], v[154:157], v[174:177], v[116:119]
	v_mfma_f32_16x16x32_bf16 v[112:115], v[166:169], v[174:177], v[112:115]
	v_mfma_f32_16x16x32_bf16 v[100:103], v[154:157], v[182:185], v[100:103]
	v_mfma_f32_16x16x32_bf16 v[96:99], v[166:169], v[182:185], v[96:99]
	v_mfma_f32_16x16x32_bf16 v[84:87], v[154:157], v[194:197], v[84:87]
	v_mfma_f32_16x16x32_bf16 v[80:83], v[166:169], v[194:197], v[80:83]
	v_mfma_f32_16x16x32_bf16 v[68:71], v[154:157], v[202:205], v[68:71]
	v_mfma_f32_16x16x32_bf16 v[64:67], v[166:169], v[202:205], v[64:67]
	v_mfma_f32_16x16x32_bf16 v[116:119], v[162:165], v[178:181], v[116:119]
	v_mfma_f32_16x16x32_bf16 v[112:115], v[170:173], v[178:181], v[112:115]
	v_mfma_f32_16x16x32_bf16 v[100:103], v[162:165], v[186:189], v[100:103]
	v_mfma_f32_16x16x32_bf16 v[96:99], v[170:173], v[186:189], v[96:99]
	v_mfma_f32_16x16x32_bf16 v[84:87], v[162:165], v[198:201], v[84:87]
	v_mfma_f32_16x16x32_bf16 v[80:83], v[170:173], v[198:201], v[80:83]
	v_mfma_f32_16x16x32_bf16 v[68:71], v[162:165], v[212:215], v[68:71]
	v_mfma_f32_16x16x32_bf16 v[64:67], v[170:173], v[212:215], v[64:67]
	s_setprio 0
	s_barrier
	s_add_i32 s5, s92, s52
	v_lshl_add_u64 v[190:191], s[46:47], 0, v[192:193]
	s_mov_b32 m0, s5
	ds_read_b128 v[174:177], v161 offset:16384
	ds_read_b128 v[178:181], v161 offset:17408
	ds_read_b128 v[182:185], v161 offset:18432
	ds_read_b128 v[186:189], v161 offset:19456
	ds_read_b128 v[194:197], v161 offset:20480
	ds_read_b128 v[198:201], v161 offset:21504
	ds_read_b128 v[202:205], v161 offset:22528
	ds_read_b128 v[212:215], v161 offset:23552
	global_load_lds_dwordx4 v[190:191], off
	s_add_i32 m0, s5, 0x2000
	s_add_u32 vcc_lo, s46, 0x40000
	v_lshl_add_u64 v[216:217], s[46:47], 0, v[144:145]
	s_addc_u32 vcc_hi, s47, 0
	s_add_i32 s4, s4, s52
	global_load_lds_dwordx4 v[216:217], off
	v_lshl_add_u64 v[218:219], vcc, 0, v[192:193]
	s_mov_b32 m0, s4
	v_lshl_add_u64 v[220:221], s[54:55], 0, v[146:147]
	global_load_lds_dwordx4 v[218:219], off
	v_lshl_add_u64 v[218:219], vcc, 0, v[144:145]
	s_add_i32 m0, s4, 0x2000
	s_nop 0
	global_load_lds_dwordx4 v[218:219], off
	v_lshl_add_u64 v[218:219], s[54:55], 0, v[148:149]
	s_mov_b32 m0, s53
	s_nop 0
	global_load_lds_dwordx4 v[218:219], off
	s_mov_b32 m0, s56
	s_nop 0
	global_load_lds_dwordx4 v[220:221], off
	s_waitcnt lgkmcnt(0)
	s_barrier
	s_setprio 1
	s_waitcnt lgkmcnt(0)
	v_mfma_f32_16x16x32_bf16 v[60:63], v[120:123], v[174:177], v[60:63]
	v_mfma_f32_16x16x32_bf16 v[56:59], v[128:131], v[174:177], v[56:59]
	v_mfma_f32_16x16x32_bf16 v[48:51], v[120:123], v[182:185], v[48:51]
	v_mfma_f32_16x16x32_bf16 v[40:43], v[128:131], v[182:185], v[40:43]
	v_mfma_f32_16x16x32_bf16 v[32:35], v[120:123], v[194:197], v[32:35]
	v_mfma_f32_16x16x32_bf16 v[24:27], v[128:131], v[194:197], v[24:27]
	v_mfma_f32_16x16x32_bf16 v[16:19], v[120:123], v[202:205], v[16:19]
	v_mfma_f32_16x16x32_bf16 v[8:11], v[128:131], v[202:205], v[8:11]
	v_mfma_f32_16x16x32_bf16 v[60:63], v[124:127], v[178:181], v[60:63]
	v_mfma_f32_16x16x32_bf16 v[56:59], v[132:135], v[178:181], v[56:59]
	v_mfma_f32_16x16x32_bf16 v[48:51], v[124:127], v[186:189], v[48:51]
	v_mfma_f32_16x16x32_bf16 v[40:43], v[132:135], v[186:189], v[40:43]
	v_mfma_f32_16x16x32_bf16 v[32:35], v[124:127], v[198:201], v[32:35]
	v_mfma_f32_16x16x32_bf16 v[24:27], v[132:135], v[198:201], v[24:27]
	v_mfma_f32_16x16x32_bf16 v[16:19], v[124:127], v[212:215], v[16:19]
	v_mfma_f32_16x16x32_bf16 v[8:11], v[132:135], v[212:215], v[8:11]
	s_setprio 0
	s_setprio 1
	v_mfma_f32_16x16x32_bf16 v[52:55], v[154:157], v[174:177], v[52:55]
	v_mfma_f32_16x16x32_bf16 v[44:47], v[166:169], v[174:177], v[44:47]
	v_mfma_f32_16x16x32_bf16 v[36:39], v[154:157], v[182:185], v[36:39]
	v_mfma_f32_16x16x32_bf16 v[28:31], v[166:169], v[182:185], v[28:31]
	v_mfma_f32_16x16x32_bf16 v[20:23], v[154:157], v[194:197], v[20:23]
	v_mfma_f32_16x16x32_bf16 v[12:15], v[166:169], v[194:197], v[12:15]
	v_mfma_f32_16x16x32_bf16 v[4:7], v[154:157], v[202:205], v[4:7]
	v_mfma_f32_16x16x32_bf16 v[0:3], v[166:169], v[202:205], v[0:3]
	v_mfma_f32_16x16x32_bf16 v[52:55], v[162:165], v[178:181], v[52:55]
	v_mfma_f32_16x16x32_bf16 v[44:47], v[170:173], v[178:181], v[44:47]
	v_mfma_f32_16x16x32_bf16 v[36:39], v[162:165], v[186:189], v[36:39]
	v_mfma_f32_16x16x32_bf16 v[28:31], v[170:173], v[186:189], v[28:31]
	v_mfma_f32_16x16x32_bf16 v[20:23], v[162:165], v[198:201], v[20:23]
	v_mfma_f32_16x16x32_bf16 v[12:15], v[170:173], v[198:201], v[12:15]
	v_mfma_f32_16x16x32_bf16 v[4:7], v[162:165], v[212:215], v[4:7]
	v_mfma_f32_16x16x32_bf16 v[0:3], v[170:173], v[212:215], v[0:3]
	s_setprio 0
	s_barrier
; #define PG8_STAGE(bufoff, gbase, voff) do { _Pragma("unroll") for (int _i = 0; _i < 2; ++_i) \
;         __builtin_amdgcn_global_load_lds((const unsigned*)((const char*)(gbase) + (voff)[_i]), (LAS unsigned*)(lds + (bufoff) + ldsw + _i * 8192), 16, 0, 0); } while (0)
; #define PG8_LDA(dst, b, h) do { _Pragma("unroll") for (int m = 0; m < 4; ++m) _Pragma("unroll") for (int k = 0; k < 2; ++k) dst[m][k] = *(const LAS bf16x8*)(lds + PG8_SA(b, h) + aoff + m * 2048 + k * 1024); } while (0)
; #define PG8_LDB(dst, b, h) do { _Pragma("unroll") for (int n = 0; n < 2; ++n) _Pragma("unroll") for (int k = 0; k < 2; ++k) dst[n][k] = *(const LAS bf16x8*)(lds + PG8_SB(b, h) + boff + n * 2048 + k * 1024); } while (0)
; #define PG8_MMA(ai, bj, At, Bt) do { __builtin_amdgcn_s_setprio(1); _Pragma("unroll") for (int m = 0; m < 4; ++m) _Pragma("unroll") for (int n = 0; n < 2; ++n) _Pragma("unroll") for (int k = 0; k < 2; ++k) \
;         acc[ai][bj][m][n] = __builtin_amdgcn_mfma_f32_16x16x32_bf16(Bt[n][k], At[m][k], acc[ai][bj][m][n], 0, 0, 0); __builtin_amdgcn_s_setprio(0); } while (0)
; #define PG8_WAIT_V(n) asm volatile("s_waitcnt vmcnt(" #n ")" ::: "memory")
; #define PG8_WAIT_L(n) asm volatile("s_waitcnt lgkmcnt(" #n ")" ::: "memory")
; #define PG8_BAR __builtin_amdgcn_s_barrier()
; #define PG8_SCHED __builtin_amdgcn_sched_barrier(0)
; template <class Epi, class Sched, bool ALIGN_EPI>
; __device__ __forceinline__ void gemm_phase(LAS unsigned char* lds, const Gemm g, const Sched& S, const Epi& E) {
;     ...
;             PG8_LDB(B0, 1, 0); PG8_LDB(B1, 1, 1); PG8_SCHED; PG8_LDA(At, 1, 0); PG8_STAGE(PG8_SA(0, 1), a2 + hstepA, voffA);
;             PG8_WAIT_V(8); PG8_WAIT_L(0); PG8_BAR; PG8_MMA(0, 0, At, B0); PG8_MMA(0, 1, At, B1); PG8_BAR; PG8_SCHED;
	s_add_i32 s4, 0, 0x18000
	s_add_i32 s5, 0, 0x1c000
	v_add_u32_e32 v132, s4, v160
	v_add_u32_e32 v170, s5, v160
	ds_read_b128 v[120:123], v132
	ds_read_b128 v[124:127], v132 offset:1024
	ds_read_b128 v[128:131], v132 offset:2048
	ds_read_b128 v[132:135], v132 offset:3072
	ds_read_b128 v[154:157], v170
	ds_read_b128 v[162:165], v170 offset:1024
	ds_read_b128 v[166:169], v170 offset:2048
	ds_read_b128 v[170:173], v170 offset:3072
	s_add_u32 s54, s54, 0x40000
	s_addc_u32 s55, s55, 0
	s_mov_b32 m0, s57
	v_lshl_add_u64 v[222:223], s[54:55], 0, v[148:149]
	ds_read_b128 v[174:177], v161 offset:32768
	ds_read_b128 v[178:181], v161 offset:33792
	ds_read_b128 v[182:185], v161 offset:34816
	ds_read_b128 v[186:189], v161 offset:35840
	ds_read_b128 v[194:197], v161 offset:36864
	ds_read_b128 v[198:201], v161 offset:37888
	ds_read_b128 v[202:205], v161 offset:38912
	ds_read_b128 v[212:215], v161 offset:39936
	global_load_lds_dwordx4 v[222:223], off
	v_lshl_add_u64 v[222:223], s[54:55], 0, v[146:147]
	s_mov_b32 m0, s58
	s_nop 0
	global_load_lds_dwordx4 v[222:223], off
	s_waitcnt vmcnt(8)
	s_waitcnt lgkmcnt(0)
	s_barrier
	s_setprio 1
	s_waitcnt lgkmcnt(0)
	v_mfma_f32_16x16x32_bf16 v[140:143], v[120:123], v[174:177], v[140:143]
	v_mfma_f32_16x16x32_bf16 v[136:139], v[128:131], v[174:177], v[136:139]
	v_mfma_f32_16x16x32_bf16 v[108:111], v[120:123], v[182:185], v[108:111]
	v_mfma_f32_16x16x32_bf16 v[104:107], v[128:131], v[182:185], v[104:107]
	v_mfma_f32_16x16x32_bf16 v[92:95], v[120:123], v[194:197], v[92:95]
	v_mfma_f32_16x16x32_bf16 v[88:91], v[128:131], v[194:197], v[88:91]
	v_mfma_f32_16x16x32_bf16 v[76:79], v[120:123], v[202:205], v[76:79]
	v_mfma_f32_16x16x32_bf16 v[72:75], v[128:131], v[202:205], v[72:75]
	v_mfma_f32_16x16x32_bf16 v[140:143], v[124:127], v[178:181], v[140:143]
	v_mfma_f32_16x16x32_bf16 v[136:139], v[132:135], v[178:181], v[136:139]
	v_mfma_f32_16x16x32_bf16 v[108:111], v[124:127], v[186:189], v[108:111]
	v_mfma_f32_16x16x32_bf16 v[104:107], v[132:135], v[186:189], v[104:107]
	v_mfma_f32_16x16x32_bf16 v[92:95], v[124:127], v[198:201], v[92:95]
	v_mfma_f32_16x16x32_bf16 v[88:91], v[132:135], v[198:201], v[88:91]
	v_mfma_f32_16x16x32_bf16 v[76:79], v[124:127], v[212:215], v[76:79]
	v_mfma_f32_16x16x32_bf16 v[72:75], v[132:135], v[212:215], v[72:75]
	s_setprio 0
	s_setprio 1
	v_mfma_f32_16x16x32_bf16 v[116:119], v[154:157], v[174:177], v[116:119]
	v_mfma_f32_16x16x32_bf16 v[112:115], v[166:169], v[174:177], v[112:115]
	v_mfma_f32_16x16x32_bf16 v[100:103], v[154:157], v[182:185], v[100:103]
	v_mfma_f32_16x16x32_bf16 v[96:99], v[166:169], v[182:185], v[96:99]
	v_mfma_f32_16x16x32_bf16 v[84:87], v[154:157], v[194:197], v[84:87]
	v_mfma_f32_16x16x32_bf16 v[80:83], v[166:169], v[194:197], v[80:83]
	v_mfma_f32_16x16x32_bf16 v[68:71], v[154:157], v[202:205], v[68:71]
	v_mfma_f32_16x16x32_bf16 v[64:67], v[166:169], v[202:205], v[64:67]
	v_mfma_f32_16x16x32_bf16 v[116:119], v[162:165], v[178:181], v[116:119]
	v_mfma_f32_16x16x32_bf16 v[112:115], v[170:173], v[178:181], v[112:115]
	v_mfma_f32_16x16x32_bf16 v[100:103], v[162:165], v[186:189], v[100:103]
	v_mfma_f32_16x16x32_bf16 v[96:99], v[170:173], v[186:189], v[96:99]
	v_mfma_f32_16x16x32_bf16 v[84:87], v[162:165], v[198:201], v[84:87]
	v_mfma_f32_16x16x32_bf16 v[80:83], v[170:173], v[198:201], v[80:83]
	v_mfma_f32_16x16x32_bf16 v[68:71], v[162:165], v[212:215], v[68:71]
	v_mfma_f32_16x16x32_bf16 v[64:67], v[170:173], v[212:215], v[64:67]
	s_setprio 0
	s_barrier
; #define PG8_STAGE(bufoff, gbase, voff) do { _Pragma("unroll") for (int _i = 0; _i < 2; ++_i) \
;         __builtin_amdgcn_global_load_lds((const unsigned*)((const char*)(gbase) + (voff)[_i]), (LAS unsigned*)(lds + (bufoff) + ldsw + _i * 8192), 16, 0, 0); } while (0)
; #define PG8_LDA(dst, b, h) do { _Pragma("unroll") for (int m = 0; m < 4; ++m) _Pragma("unroll") for (int k = 0; k < 2; ++k) dst[m][k] = *(const LAS bf16x8*)(lds + PG8_SA(b, h) + aoff + m * 2048 + k * 1024); } while (0)
; #define PG8_MMA(ai, bj, At, Bt) do { __builtin_amdgcn_s_setprio(1); _Pragma("unroll") for (int m = 0; m < 4; ++m) _Pragma("unroll") for (int n = 0; n < 2; ++n) _Pragma("unroll") for (int k = 0; k < 2; ++k) \
;         acc[ai][bj][m][n] = __builtin_amdgcn_mfma_f32_16x16x32_bf16(Bt[n][k], At[m][k], acc[ai][bj][m][n], 0, 0, 0); __builtin_amdgcn_s_setprio(0); } while (0)
; #define PG8_WAIT_V(n) asm volatile("s_waitcnt vmcnt(" #n ")" ::: "memory")
; #define PG8_WAIT_L(n) asm volatile("s_waitcnt lgkmcnt(" #n ")" ::: "memory")
; #define PG8_BAR __builtin_amdgcn_s_barrier()
; #define PG8_SCHED __builtin_amdgcn_sched_barrier(0)
; template <class Epi, class Sched, bool ALIGN_EPI>
; __device__ __forceinline__ void gemm_phase(LAS unsigned char* lds, const Gemm g, const Sched& S, const Epi& E) {
;     ...
;         for (int t = 0; t < nt; t += 2) {
;     ...
;             PG8_LDA(At, 1, 1); PG8_STAGE(PG8_SB(1, 0), b3, voffB); PG8_STAGE(PG8_SB(1, 1), b3 + hstepB, voffB); PG8_STAGE(PG8_SA(1, 0), a3, voffA);
;             PG8_WAIT_V(8); PG8_WAIT_L(0); PG8_BAR; PG8_MMA(1, 0, At, B0); PG8_MMA(1, 1, At, B1); PG8_BAR; PG8_SCHED;
	s_add_i32 s4, s4, s52
	v_lshl_add_u64 v[190:191], v[190:191], 0, s[12:13]
	s_mov_b32 m0, s4
	ds_read_b128 v[174:177], v161 offset:49152
	ds_read_b128 v[178:181], v161 offset:50176
	ds_read_b128 v[182:185], v161 offset:51200
	ds_read_b128 v[186:189], v161 offset:52224
	ds_read_b128 v[194:197], v161 offset:53248
	ds_read_b128 v[198:201], v161 offset:54272
	ds_read_b128 v[202:205], v161 offset:55296
	ds_read_b128 v[212:215], v161 offset:56320
	global_load_lds_dwordx4 v[190:191], off
	s_add_i32 m0, s4, 0x2000
	s_add_u32 s46, s46, 0x40080
	v_lshl_add_u64 v[190:191], v[216:217], 0, s[12:13]
	s_addc_u32 s47, s47, 0
	s_add_i32 s4, s5, s52
	global_load_lds_dwordx4 v[190:191], off
	v_lshl_add_u64 v[190:191], s[46:47], 0, v[192:193]
	s_mov_b32 m0, s4
	s_nop 0
	global_load_lds_dwordx4 v[190:191], off
	v_lshl_add_u64 v[190:191], s[46:47], 0, v[144:145]
	s_add_i32 m0, s4, 0x2000
	s_nop 0
	global_load_lds_dwordx4 v[190:191], off
	v_lshl_add_u64 v[190:191], v[218:219], 0, s[12:13]
	s_mov_b32 m0, s65
	s_nop 0
	global_load_lds_dwordx4 v[190:191], off
	v_lshl_add_u64 v[190:191], v[220:221], 0, s[12:13]
	s_mov_b32 m0, s66
	s_nop 0
	global_load_lds_dwordx4 v[190:191], off
	s_waitcnt vmcnt(8)
	s_waitcnt lgkmcnt(0)
	s_barrier
	s_setprio 1
	s_waitcnt lgkmcnt(0)
	v_mfma_f32_16x16x32_bf16 v[60:63], v[120:123], v[174:177], v[60:63]
	v_mfma_f32_16x16x32_bf16 v[56:59], v[128:131], v[174:177], v[56:59]
	v_mfma_f32_16x16x32_bf16 v[48:51], v[120:123], v[182:185], v[48:51]
	v_mfma_f32_16x16x32_bf16 v[40:43], v[128:131], v[182:185], v[40:43]
	v_mfma_f32_16x16x32_bf16 v[32:35], v[120:123], v[194:197], v[32:35]
	v_mfma_f32_16x16x32_bf16 v[24:27], v[128:131], v[194:197], v[24:27]
	v_mfma_f32_16x16x32_bf16 v[16:19], v[120:123], v[202:205], v[16:19]
	v_mfma_f32_16x16x32_bf16 v[8:11], v[128:131], v[202:205], v[8:11]
	v_mfma_f32_16x16x32_bf16 v[60:63], v[124:127], v[178:181], v[60:63]
	v_mfma_f32_16x16x32_bf16 v[56:59], v[132:135], v[178:181], v[56:59]
	v_mfma_f32_16x16x32_bf16 v[48:51], v[124:127], v[186:189], v[48:51]
	v_mfma_f32_16x16x32_bf16 v[40:43], v[132:135], v[186:189], v[40:43]
	v_mfma_f32_16x16x32_bf16 v[32:35], v[124:127], v[198:201], v[32:35]
	v_mfma_f32_16x16x32_bf16 v[24:27], v[132:135], v[198:201], v[24:27]
	v_mfma_f32_16x16x32_bf16 v[16:19], v[124:127], v[212:215], v[16:19]
	v_mfma_f32_16x16x32_bf16 v[8:11], v[132:135], v[212:215], v[8:11]
	s_setprio 0
	s_setprio 1
	v_mfma_f32_16x16x32_bf16 v[52:55], v[154:157], v[174:177], v[52:55]
	v_mfma_f32_16x16x32_bf16 v[44:47], v[166:169], v[174:177], v[44:47]
	v_mfma_f32_16x16x32_bf16 v[36:39], v[154:157], v[182:185], v[36:39]
	v_mfma_f32_16x16x32_bf16 v[28:31], v[166:169], v[182:185], v[28:31]
	v_mfma_f32_16x16x32_bf16 v[20:23], v[154:157], v[194:197], v[20:23]
	v_mfma_f32_16x16x32_bf16 v[12:15], v[166:169], v[194:197], v[12:15]
	v_mfma_f32_16x16x32_bf16 v[4:7], v[154:157], v[202:205], v[4:7]
	v_mfma_f32_16x16x32_bf16 v[0:3], v[166:169], v[202:205], v[0:3]
	v_mfma_f32_16x16x32_bf16 v[52:55], v[162:165], v[178:181], v[52:55]
	v_mfma_f32_16x16x32_bf16 v[44:47], v[170:173], v[178:181], v[44:47]
	v_mfma_f32_16x16x32_bf16 v[36:39], v[162:165], v[186:189], v[36:39]
	v_mfma_f32_16x16x32_bf16 v[28:31], v[170:173], v[186:189], v[28:31]
	v_mfma_f32_16x16x32_bf16 v[20:23], v[162:165], v[198:201], v[20:23]
	v_mfma_f32_16x16x32_bf16 v[12:15], v[170:173], v[198:201], v[12:15]
	v_mfma_f32_16x16x32_bf16 v[4:7], v[162:165], v[212:215], v[4:7]
	v_mfma_f32_16x16x32_bf16 v[0:3], v[170:173], v[212:215], v[0:3]
	s_setprio 0
	s_barrier
	s_add_i32 s91, s91, 2
	s_add_u32 s44, s44, 0x100
	s_addc_u32 s45, s45, 0
	s_add_u32 s87, s87, 0x100
	s_addc_u32 s90, s90, 0
	s_cmp_gt_u32 s91, 13
